# P1 modulate row loop: same hoist of the gain/scale/shift loads of column blocks 1..3 as in P7
# baseline (speedup 1.0000x reference)
; __device__ __forceinline__ unsigned pk2(float lo, float hi) { return cvt_pk_bf16(lo, hi); }
; template <int WHICH> __device__ __forceinline__ void phase_modulate(const Params& P, const Ctx& C) {
;     ...
;     for (int r = gw; r < NR; r += NGW) {
;         const float* xr = (WHICH == 0) ? (r < NPR ? P.in[0] + (size_t)r * DM : P.in[1] + (size_t)(r - NPR) * DM) : (const float*)(ws + WS_X1) + (size_t)r * DM;
;         const float* mr = MOD + (size_t)pg8::mod_row(r) * 6144 + (WHICH == 0 ? 0 : 3072);
;         f32x4 v[4]; float ss = 0.f;
; #pragma unroll
;         for (int j = 0; j < 4; ++j) { v[j] = *(const f32x4*)(xr + 4 * lane + 256 * j); ss += (v[j][0] * v[j][0] + v[j][1] * v[j][1]) + (v[j][2] * v[j][2] + v[j][3] * v[j][3]); }
;         const float rstd = 1.0f / sqrtf(wave_sum(ss) * (1.f / DM) + EPS);
; #pragma unroll
;         for (int j = 0; j < 4; ++j) { const int c = 4 * lane + 256 * j;
;             const f32x4 g = *(const f32x4*)(gn + c), sh = *(const f32x4*)(mr + c), sc = *(const f32x4*)(mr + 1024 + c);
;             const f32x4 o = v[j] * rstd * g * (sc + 1.0f) + sh;
;             u32x2 w; w.x = pk2(o[0], o[1]); w.y = pk2(o[2], o[3]);
;             *(u32x2*)(H + (size_t)r * DM + c) = w; }
;     }
.LBB0_211:
	v_lshl_add_u64 v[30:31], s[22:23], 0, v[8:9]
	global_load_dwordx4 v[18:21], v[30:31], off
	global_load_dwordx4 v[22:25], v[30:31], off offset:1024
	global_load_dwordx4 v[0:3], v[30:31], off offset:3072
	global_load_dwordx4 v[26:29], v[30:31], off offset:2048
	s_lshr_b32 s14, s14, 2
	s_ashr_i32 s22, s10, 13
	s_add_i32 s14, s14, 2
	s_and_b64 s[20:21], s[20:21], exec
	s_cselect_b32 s14, s22, s14
	s_mul_hi_i32 s21, s14, 0x6000
	s_mulk_i32 s14, 0x6000
	s_add_u32 s20, s0, s14
	s_addc_u32 s21, s1, s21
	v_lshl_add_u64 v[42:43], s[20:21], 0, v[8:9]
	v_lshl_add_u64 v[62:63], v[42:43], 0, s[18:19]
	v_add_co_u32_e32 v44, vcc, s27, v42
	s_lshl_b64 s[2:3], s[2:3], 11
	s_nop 0
	v_addc_co_u32_e32 v45, vcc, 0, v43, vcc
	global_load_dwordx4 v[30:33], v[44:45], off
	global_load_dwordx4 v[34:37], v[42:43], off
	global_load_dwordx4 v[38:41], v[4:5], off
	global_load_dwordx4 v[64:67], v[4:5], off offset:1024
	global_load_dwordx4 v[68:71], v[62:63], off offset:1024
	global_load_dwordx4 v[72:75], v[42:43], off offset:1024
	global_load_dwordx4 v[76:79], v[4:5], off offset:2048
	global_load_dwordx4 v[80:83], v[62:63], off offset:2048
	global_load_dwordx4 v[84:87], v[42:43], off offset:2048
	global_load_dwordx4 v[88:91], v[4:5], off offset:3072
	global_load_dwordx4 v[92:95], v[62:63], off offset:3072
	global_load_dwordx4 v[96:99], v[42:43], off offset:3072
	s_add_u32 s10, s10, s12
	s_addc_u32 s11, s11, s13
	s_add_u32 s4, s4, s16
	s_addc_u32 s5, s5, s17
	s_cmpk_lt_i32 s10, 0x4200
	s_waitcnt vmcnt(15)
	v_pk_mul_f32 v[44:45], v[20:21], v[20:21]
	v_pk_mul_f32 v[46:47], v[18:19], v[18:19]
	s_waitcnt vmcnt(14)
	v_pk_mul_f32 v[48:49], v[24:25], v[24:25]
	v_pk_mul_f32 v[50:51], v[22:23], v[22:23]
	v_pk_mov_b32 v[56:57], v[46:47], v[44:45] op_sel:[1,0]
	v_mov_b32_e32 v47, v45
	v_pk_mov_b32 v[44:45], v[50:51], v[48:49] op_sel:[1,0]
	v_mov_b32_e32 v51, v49
	s_waitcnt vmcnt(13)
	v_mul_f32_e32 v55, v0, v0
	s_waitcnt vmcnt(12)
	v_mul_f32_e32 v52, v27, v27
	v_mul_f32_e32 v54, v29, v29
	v_pk_add_f32 v[46:47], v[56:57], v[46:47]
	v_pk_add_f32 v[44:45], v[44:45], v[50:51]
	v_mul_f32_e32 v58, v1, v1
	v_mul_f32_e32 v59, v2, v2
	v_mul_f32_e32 v60, v3, v3
	v_pk_fma_f32 v[48:49], v[26:27], v[26:27], v[52:53] op_sel_hi:[1,1,0]
	v_pk_fma_f32 v[52:53], v[28:29], v[28:29], v[54:55] op_sel_hi:[1,1,0]
	v_pk_add_f32 v[46:47], v[46:47], v[46:47] op_sel:[0,1] op_sel_hi:[1,0]
	v_pk_add_f32 v[44:45], v[44:45], v[44:45] op_sel:[0,1] op_sel_hi:[1,0]
	v_mov_b32_e32 v49, v59
	v_mov_b32_e32 v53, v60
	v_mov_b32_e32 v47, v55
	v_mov_b32_e32 v45, v58
	v_pk_add_f32 v[48:49], v[48:49], v[52:53]
	v_pk_add_f32 v[44:45], v[46:47], v[44:45]
	s_waitcnt vmcnt(11)
	v_pk_add_f32 v[30:31], v[30:31], 1.0 op_sel_hi:[1,0]
	v_pk_add_f32 v[44:45], v[44:45], v[48:49]
	v_pk_add_f32 v[32:33], v[32:33], 1.0 op_sel_hi:[1,0]
	v_add_f32_e32 v44, v44, v45
	ds_bpermute_b32 v45, v10, v44
	s_waitcnt lgkmcnt(0)
	v_add_f32_e32 v44, v44, v45
	ds_bpermute_b32 v45, v11, v44
	s_waitcnt lgkmcnt(0)
	v_add_f32_e32 v44, v44, v45
	ds_bpermute_b32 v45, v12, v44
	s_waitcnt lgkmcnt(0)
	v_add_f32_e32 v44, v44, v45
	ds_bpermute_b32 v45, v13, v44
	s_waitcnt lgkmcnt(0)
	v_add_f32_e32 v44, v44, v45
	ds_bpermute_b32 v45, v14, v44
	s_waitcnt lgkmcnt(0)
	v_add_f32_e32 v44, v44, v45
	ds_bpermute_b32 v45, v15, v44
	s_waitcnt lgkmcnt(0)
	v_add_f32_e32 v44, v44, v45
	v_fmamk_f32 v44, v44, 0x3a800000, v16
	v_mul_f32_e32 v45, 0x4f800000, v44
	v_cmp_gt_f32_e32 vcc, s26, v44
	s_nop 1
	v_cndmask_b32_e32 v46, v44, v45, vcc
	v_sqrt_f32_e32 v47, v46
	v_lshl_add_u64 v[44:45], v[6:7], 0, s[2:3]
	v_add_u32_e32 v48, -1, v47
	v_add_u32_e32 v49, 1, v47
	v_fma_f32 v50, -v48, v47, v46
	v_fma_f32 v51, -v49, v47, v46
	v_cmp_ge_f32_e64 s[2:3], 0, v50
	s_nop 1
	v_cndmask_b32_e64 v47, v47, v48, s[2:3]
	v_cmp_lt_f32_e64 s[2:3], 0, v51
	s_nop 1
	v_cndmask_b32_e64 v47, v47, v49, s[2:3]
	v_mul_f32_e32 v48, 0x37800000, v47
	v_cndmask_b32_e32 v47, v47, v48, vcc
	v_cmp_class_f32_e32 vcc, v46, v17
	s_nop 1
	v_cndmask_b32_e32 v46, v47, v46, vcc
	v_div_scale_f32 v47, s[2:3], v46, v46, 1.0
	v_rcp_f32_e32 v48, v47
	v_div_scale_f32 v49, vcc, 1.0, v46, 1.0
	v_fma_f32 v50, -v47, v48, 1.0
	v_fmac_f32_e32 v48, v50, v48
	v_mul_f32_e32 v50, v49, v48
	v_fma_f32 v51, -v47, v50, v49
	v_fmac_f32_e32 v50, v51, v48
	v_fma_f32 v47, -v47, v50, v49
	v_div_fmas_f32 v47, v47, v48, v50
	v_div_fixup_f32 v46, v47, v46, 1.0
	v_pk_mul_f32 v[18:19], v[18:19], v[46:47] op_sel_hi:[1,0]
	v_pk_mul_f32 v[20:21], v[20:21], v[46:47] op_sel_hi:[1,0]
	s_waitcnt vmcnt(0)
	v_pk_mul_f32 v[18:19], v[38:39], v[18:19]
	v_pk_mul_f32 v[20:21], v[40:41], v[20:21]
	v_pk_fma_f32 v[18:19], v[30:31], v[18:19], v[34:35]
	v_pk_fma_f32 v[20:21], v[32:33], v[20:21], v[36:37]
	v_cvt_pk_bf16_f32 v18, v18, v19
	v_lshl_add_u64 v[38:39], v[42:43], 0, s[18:19]
	v_cvt_pk_bf16_f32 v19, v20, v21
	global_store_dwordx2 v[44:45], v[18:19], off
	s_nop 0
	v_pk_mul_f32 v[24:25], v[24:25], v[46:47] op_sel_hi:[1,0]
	v_pk_mul_f32 v[22:23], v[22:23], v[46:47] op_sel_hi:[1,0]
	v_pk_mul_f32 v[26:27], v[26:27], v[46:47] op_sel_hi:[1,0]
	v_pk_mul_f32 v[28:29], v[28:29], v[46:47] op_sel_hi:[1,0]
	v_pk_mul_f32 v[2:3], v[2:3], v[46:47] op_sel_hi:[1,0]
	v_pk_mul_f32 v[0:1], v[0:1], v[46:47] op_sel_hi:[1,0]
	v_pk_mul_f32 v[18:19], v[64:65], v[22:23]
	v_pk_mul_f32 v[20:21], v[66:67], v[24:25]
	v_pk_add_f32 v[24:25], v[68:69], 1.0 op_sel_hi:[1,0]
	v_pk_add_f32 v[22:23], v[70:71], 1.0 op_sel_hi:[1,0]
	v_pk_fma_f32 v[18:19], v[24:25], v[18:19], v[72:73]
	v_pk_fma_f32 v[20:21], v[22:23], v[20:21], v[74:75]
	v_cvt_pk_bf16_f32 v18, v18, v19
	s_nop 0
	v_cvt_pk_bf16_f32 v19, v20, v21
	global_store_dwordx2 v[44:45], v[18:19], off offset:512
	s_nop 0
	v_pk_mul_f32 v[18:19], v[26:27], v[76:77]
	v_pk_add_f32 v[22:23], v[80:81], 1.0 op_sel_hi:[1,0]
	v_pk_mul_f32 v[20:21], v[28:29], v[78:79]
	v_pk_add_f32 v[24:25], v[82:83], 1.0 op_sel_hi:[1,0]
	v_pk_fma_f32 v[18:19], v[18:19], v[22:23], v[84:85]
	v_pk_fma_f32 v[20:21], v[20:21], v[24:25], v[86:87]
	v_cvt_pk_bf16_f32 v18, v18, v19
	s_nop 0
	v_cvt_pk_bf16_f32 v19, v20, v21
	global_store_dwordx2 v[44:45], v[18:19], off offset:1024
	s_nop 0
	v_pk_mul_f32 v[0:1], v[0:1], v[88:89]
	v_pk_mul_f32 v[2:3], v[2:3], v[90:91]
	v_pk_add_f32 v[20:21], v[92:93], 1.0 op_sel_hi:[1,0]
	v_pk_add_f32 v[18:19], v[94:95], 1.0 op_sel_hi:[1,0]
	v_pk_fma_f32 v[0:1], v[0:1], v[20:21], v[96:97]
	v_pk_fma_f32 v[2:3], v[2:3], v[18:19], v[98:99]
	v_cvt_pk_bf16_f32 v0, v0, v1
	s_nop 0
	v_cvt_pk_bf16_f32 v1, v2, v3
	global_store_dwordx2 v[44:45], v[0:1], off offset:1536
	s_cbranch_scc0 .LBB0_216
